# grid barrier: sharded release - the last XCD leader bumps all per-XCD generation words itself; every workgroup polls its own XCD word (32 pollers per line)
# baseline (speedup 1.0000x reference)
; __device__ __forceinline__ unsigned xb_ld(unsigned* p)              { return __hip_atomic_load(p, __ATOMIC_RELAXED, __HIP_MEMORY_SCOPE_AGENT); }
; __device__ __forceinline__ unsigned xb_add(unsigned* p, unsigned v) { return __hip_atomic_fetch_add(p, v, __ATOMIC_RELAXED, __HIP_MEMORY_SCOPE_AGENT); }
; #define XB_SPIN(cond, bar) do { unsigned _sp = 0; while (cond) { __builtin_amdgcn_s_sleep(1); \
;     if ((++_sp & 255u) == 0u) { if (xb_ld(&(bar)[XB_TMO])) break; if (_sp > XB_SPIN_CAP) { atomicAdd(&(bar)[XB_TMO], 1u); break; } } } } while (0)
; __device__ __forceinline__ void xcd_barrier(const XcdBarrier& b) {
;     ...
;             const unsigned og = xb_add(&bar[XB_TOP], 1u);
;             const unsigned tg = og / nx;
;             if (og + 1u == (tg + 1u) * nx) xb_add(&bar[XB_TOPGEN], 1u);
;             else XB_SPIN(xb_ld(&bar[XB_TOPGEN]) == tg, bar);
.LBB0_57:
	s_or_b64 exec, exec, s[16:17]
	v_cvt_f32_u32_e32 v4, v0
	s_waitcnt vmcnt(0)
	v_readfirstlane_b32 s3, v3
	v_sub_u32_e32 v3, 0, v0
	v_readlane_b32 s10, v252, 14
	v_rcp_iflag_f32_e32 v4, v4
	v_add_u32_e32 v2, s3, v2
	v_add_u32_e32 v5, 1, v2
	v_readlane_b32 s11, v252, 15
	v_mul_f32_e32 v4, 0x4f7ffffe, v4
	v_cvt_u32_f32_e32 v4, v4
	s_mov_b64 s[16:17], -1
	v_mul_lo_u32 v3, v3, v4
	v_mul_hi_u32 v3, v4, v3
	v_add_u32_e32 v3, v4, v3
	v_mul_hi_u32 v3, v2, v3
	v_mul_lo_u32 v4, v3, v0
	v_sub_u32_e32 v2, v2, v4
	v_add_u32_e32 v6, 1, v3
	v_sub_u32_e32 v4, v2, v0
	v_cmp_ge_u32_e32 vcc, v2, v0
	s_nop 1
	v_cndmask_b32_e32 v3, v3, v6, vcc
	v_cndmask_b32_e32 v2, v2, v4, vcc
	v_add_u32_e32 v4, 1, v3
	v_cmp_ge_u32_e32 vcc, v2, v0
	s_nop 1
	v_cndmask_b32_e32 v4, v3, v4, vcc
	v_mul_lo_u32 v2, v0, v4
	v_add_u32_e32 v0, v2, v0
	v_cmp_ne_u32_e32 vcc, v5, v0
	v_mov_b64_e32 v[2:3], s[10:11]
	s_and_saveexec_b64 s[10:11], vcc
	s_cbranch_execz .Lxb_last
	v_readlane_b32 s14, v252, 10
	v_readlane_b32 s15, v252, 11
	s_mov_b64 s[18:19], 0
	s_nop 3
	global_load_dword v0, v1, s[14:15] sc1
	s_waitcnt vmcnt(0)
	v_cmp_eq_u32_e32 vcc, v0, v4
	s_and_saveexec_b64 s[16:17], vcc
	s_cbranch_execz .LBB0_68
	s_mov_b32 s3, 1
	s_branch .LBB0_61

; __device__ __forceinline__ unsigned xb_ld(unsigned* p)              { return __hip_atomic_load(p, __ATOMIC_RELAXED, __HIP_MEMORY_SCOPE_AGENT); }
; #define XB_SPIN(cond, bar) do { unsigned _sp = 0; while (cond) { __builtin_amdgcn_s_sleep(1); \
;     if ((++_sp & 255u) == 0u) { if (xb_ld(&(bar)[XB_TMO])) break; if (_sp > XB_SPIN_CAP) { atomicAdd(&(bar)[XB_TMO], 1u); break; } } } } while (0)
; __device__ __forceinline__ void xcd_barrier(const XcdBarrier& b) {
;     ...
;             else XB_SPIN(xb_ld(&bar[XB_TOPGEN]) == tg, bar);
.LBB0_65:
	v_readlane_b32 s14, v252, 10
	v_readlane_b32 s15, v252, 11
	s_add_i32 s3, s3, 1
	s_mov_b64 s[38:39], -1
	s_nop 2
	global_load_dword v0, v1, s[14:15] sc1
	s_waitcnt vmcnt(0)
	v_cmp_ne_u32_e32 vcc, v0, v4
	s_orn2_b64 s[36:37], vcc, exec
	s_branch .LBB0_60

; __device__ __forceinline__ unsigned xb_ld(unsigned* p)              { return __hip_atomic_load(p, __ATOMIC_RELAXED, __HIP_MEMORY_SCOPE_AGENT); }
; __device__ __forceinline__ unsigned xb_add(unsigned* p, unsigned v) { return __hip_atomic_fetch_add(p, v, __ATOMIC_RELAXED, __HIP_MEMORY_SCOPE_AGENT); }
; #define XB_SPIN(cond, bar) do { unsigned _sp = 0; while (cond) { __builtin_amdgcn_s_sleep(1); \
;     if ((++_sp & 255u) == 0u) { if (xb_ld(&(bar)[XB_TMO])) break; if (_sp > XB_SPIN_CAP) { atomicAdd(&(bar)[XB_TMO], 1u); break; } } } } while (0)
; __device__ __forceinline__ void xcd_barrier(const XcdBarrier& b) {
;     ...
;             if (og + 1u == (tg + 1u) * nx) xb_add(&bar[XB_TOPGEN], 1u);
;             else XB_SPIN(xb_ld(&bar[XB_TOPGEN]) == tg, bar);
;             __builtin_amdgcn_fence(__ATOMIC_ACQUIRE, "agent");
;             xb_add(&bar[XB_XGEN(b.x)], 1u);
;             asm volatile("s_waitcnt vmcnt(0)" ::: "memory");
.LBB0_68:
	s_or_b64 exec, exec, s[16:17]
	v_readlane_b32 s14, v251, 6
	v_readlane_b32 s15, v251, 7
	s_orn2_b64 s[16:17], s[18:19], exec
	s_nop 0
	v_mov_b64_e32 v[2:3], s[14:15]
	s_branch .LBB0_69
.Lxb_last:
	s_or_b64 exec, exec, s[10:11]
	v_readlane_b32 s14, v252, 12
	v_readlane_b32 s15, v252, 13
	s_nop 0
	s_sub_u32 s14, s14, 0x1000
	s_subb_u32 s15, s15, 0
	s_nop 3
	global_atomic_add v1, v188, s[14:15]
	global_atomic_add v1, v188, s[14:15] offset:256
	global_atomic_add v1, v188, s[14:15] offset:512
	global_atomic_add v1, v188, s[14:15] offset:768
	global_atomic_add v1, v188, s[14:15] offset:1024
	global_atomic_add v1, v188, s[14:15] offset:1280
	global_atomic_add v1, v188, s[14:15] offset:1536
	global_atomic_add v1, v188, s[14:15] offset:1792
	global_atomic_add v1, v188, s[14:15] offset:2048
	global_atomic_add v1, v188, s[14:15] offset:2304
	global_atomic_add v1, v188, s[14:15] offset:2560
	global_atomic_add v1, v188, s[14:15] offset:2816
	global_atomic_add v1, v188, s[14:15] offset:3072
	global_atomic_add v1, v188, s[14:15] offset:3328
	global_atomic_add v1, v188, s[14:15] offset:3584
	global_atomic_add v1, v188, s[14:15] offset:3840
	s_branch .LBB0_71
